# C_align0 + GEMM phases: per-block s_setprio flips removed, one static s_setprio 1 for waves 4-7 (strategy 4: static priority for the younger half)
# baseline (speedup 1.0000x reference)
;     __device__ bool next(int i, Unit& u) const { if (i != 0) return false; return so.next(round, u); }
;     __device__ __forceinline__ bool next(int i, Unit& u) const { if (i > 0 || !on) return false; u.pm = pm; u.pn = 0; return true; }
;     __host__ __device__ bool next(int i, Unit& u) const {
;         const long L = (long)i * G + c; if (L >= nwg) return false;
;         int wgid = (int)L; { const int q = nwg / NXCD, r = nwg % NXCD, xcd = wgid % NXCD, off = wgid / NXCD; wgid = (xcd < r ? xcd * (q + 1) : r * (q + 1) + (xcd - r) * q) + off; }
;         const int nig = WGM * nN, gid = wgid / nig, fm = gid * WGM, gsz = (nM - fm) < WGM ? (nM - fm) : WGM;
;         u.pm = fm + ((wgid % nig) % gsz); u.pn = (wgid % nig) / gsz; return true;
.LBB0_180:
	s_or_b64 exec, exec, s[0:1]
	s_cmp_lt_u32 s84, 4
	s_cbranch_scc1 .Lprio_p1
	s_setprio 1
.Lprio_p1:
	v_readlane_b32 s3, v243, 2
	s_cmpk_lt_i32 s3, 0xa00
	v_mov_b32_e32 v8, v220
	s_cselect_b64 s[0:1], -1, 0
	s_cmpk_gt_i32 s3, 0x9ff
	s_waitcnt lgkmcnt(0)
	s_barrier
	s_cbranch_scc1 .LBB0_182
	v_readlane_b32 s5, v243, 2
	s_ashr_i32 s3, s5, 31
	s_lshr_b32 s3, s3, 29
	s_add_i32 s3, s5, s3
	s_ashr_i32 s4, s3, 3
	s_and_b32 s3, s3, -8
	s_sub_i32 s3, s5, s3
	s_cmp_lt_i32 s3, 0
	s_movk_i32 s5, 0x141
	s_cselect_b32 s5, s5, 0x140
	s_mul_i32 s3, s3, s5
	s_add_i32 s3, s3, s4
	s_mul_hi_i32 s4, s3, 0x66666667
	s_lshr_b32 s5, s4, 31
	s_ashr_i32 s4, s4, 6
	s_add_i32 s4, s4, s5
	s_lshl_b32 s5, s4, 3
	s_mulk_i32 s4, 0xa0
	s_sub_i32 s3, s3, s4
	s_sext_i32_i16 s4, s3
	s_bfe_u32 s4, s4, 0x3001c
	s_add_i32 s4, s3, s4
	s_sext_i32_i16 s6, s4
	s_and_b32 s4, s4, 0xfff8
	s_sub_i32 s3, s3, s4
	s_sext_i32_i16 s3, s3
	s_add_i32 s4, s5, s3
	s_ashr_i32 s46, s6, 3

; __device__ __forceinline__ void phase2a(const Params& p, int gw, int NGW, int lane) {
;     bf16* kir = (bf16*)((unsigned char*)p.out + DO_KIR); float* wis = (float*)((unsigned char*)p.out + DO_WIS); const float* kwp = (const float*)((const unsigned char*)p.out + DO_KWP);
;     const float* tab = (const float*)(p.ws + WS_ROPE);
;     const float kg = p.kln_g[lane], kb = p.kln_b[lane];
;     const int rem = lane & 31; const int ppos = 32 * (rem >> 4) + 8 * ((rem >> 2) & 3) + 4 * (lane >> 5) + (rem & 3);
;     for (int tok0 = gw; tok0 < M; tok0 += 4 * NGW) {
;         float kiv[4], wv[4];
; #pragma unroll
;         for (int u = 0; u < 4; ++u) { const int tok = tok0 + u * NGW < M ? tok0 + u * NGW : tok0;
;             const float* kw0 = kwp + (size_t)tok * 80; const float* kw1 = kw0 + (size_t)M * 80;
;             kiv[u] = kw0[lane] + kw1[lane]; wv[u] = lane < 8 ? kw0[64 + lane] + kw1[64 + lane] : 0.f; }
; #pragma unroll
.LBB0_432:
	s_or_b64 exec, exec, s[0:1]
	s_setprio 0
	v_mov_b32_e32 v2, v167
	s_andn2_b64 vcc, exec, s[20:21]
	v_xor_b32_e32 v221, 32, v220
	v_and_b32_e32 v222, 64, v220
	s_waitcnt lgkmcnt(0)
	s_barrier
	s_cbranch_vccnz .LBB0_457
	v_and_b32_e32 v8, 63, v2
	v_readlane_b32 s36, v243, 8
	v_lshlrev_b32_e32 v0, 2, v8
	v_readlane_b32 s37, v243, 9
	v_readlane_b32 s38, v243, 10
	v_readlane_b32 s39, v243, 11
	v_readlane_b32 s40, v243, 12
	v_readlane_b32 s41, v243, 13
	v_readlane_b32 s42, v243, 14
	v_readlane_b32 s43, v243, 15
	v_readlane_b32 s44, v243, 16
	v_readlane_b32 s45, v243, 17
	v_readlane_b32 s46, v243, 18
	v_readlane_b32 s47, v243, 19
	v_readlane_b32 s48, v243, 20
	v_readlane_b32 s49, v243, 21
	v_readlane_b32 s50, v243, 22
	v_readlane_b32 s51, v243, 23
	global_load_dword v16, v0, s[36:37]
	v_readlane_b32 s36, v243, 32
	v_readlane_b32 s50, v243, 46
	v_readlane_b32 s51, v243, 47
	v_and_b32_e32 v18, 31, v2
	v_lshrrev_b32_e32 v1, 3, v2
	v_and_b32_e32 v4, 3, v2
	v_lshlrev_b32_e32 v2, 7, v2
	v_mov_b32_e32 v3, 0
	global_load_dword v17, v0, s[50:51]
	v_and_b32_e32 v2, 0xe00, v2
	v_lshl_add_u64 v[6:7], s[80:81], 0, v[2:3]
	s_mov_b64 s[6:7], 0x1000000
	v_readlane_b32 s48, v243, 44
	v_lshl_add_u64 v[6:7], v[6:7], 0, s[6:7]
	s_lshl_b32 s3, s85, 6
	s_lshl_b32 s6, s84, 3
	s_add_i32 s48, s3, s6
	s_lshl_b32 s3, s85, 8
	s_lshl_b32 s6, s84, 5
	v_readlane_b32 s49, v243, 45
	s_add_i32 s50, s3, s6
	s_ashr_i32 s3, s2, 31
	s_lshl_b32 s8, s87, 5
	s_lshl_b32 s49, s87, 8
	s_lshl_b32 s51, s87, 10
	s_lshl_b32 s52, s87, 4
	s_lshl_b32 s53, s87, 7
	s_lshl_b32 s54, s87, 9
	s_lshl_b32 s58, s87, 6
	s_lshl_b64 s[6:7], s[2:3], 5
	s_add_u32 s3, s80, s6
	s_addc_u32 s6, s81, s7
	s_add_u32 s20, s3, 0x1400000
	v_add_u32_e32 v2, 64, v222
	s_addc_u32 s21, s6, 0
	s_ashr_i32 s9, s8, 31
	v_and_or_b32 v10, v1, 4, v4
	v_mov_b32_e32 v1, v3
	v_cmp_lt_i32_e32 vcc, v221, v2
	s_lshl_b64 s[22:23], s[8:9], 5
	s_mul_i32 s6, s2, 0x140
	v_or_b32_e32 v12, 64, v8
	v_lshl_add_u64 v[4:5], s[80:81], 0, v[0:1]
	s_mov_b64 s[4:5], 0x1400000
	v_cndmask_b32_e32 v2, v220, v221, vcc
	s_mul_hi_i32 s3, s2, 0x140
	s_add_u32 s24, s80, s6
	v_lshlrev_b32_e32 v10, 1, v10
	v_cmp_gt_u32_e64 s[0:1], 8, v8
	v_lshl_add_u64 v[4:5], v[4:5], 0, s[4:5]
	v_cmp_gt_u32_e64 s[4:5], 32, v8
	v_lshlrev_b32_e32 v19, 2, v2
	s_mul_i32 s55, s87, 24
	s_mul_i32 s56, s87, 0xc0
	s_mul_i32 s57, s87, 0x300
	s_addc_u32 s25, s81, s3
	s_mul_i32 s3, s87, 0x2800
	s_mul_hi_i32 s9, s8, 0x140
	s_mov_b32 s29, 0
	v_lshlrev_b32_e32 v8, 2, v8
	v_mov_b32_e32 v9, v3
	v_mov_b32_e32 v20, 0xbc800000
	v_mov_b32_e32 v21, 0x3727c5ac
	v_mov_b32_e32 v22, 0x3c800000
	s_mov_b32 s59, 0xf800000
	v_mov_b32_e32 v23, 0x260
	s_mov_b32 s60, 0x80000
	s_movk_i32 s61, 0x7fff
	v_lshlrev_b32_e32 v24, 2, v12
	v_mov_b32_e32 v12, v10
	v_mov_b32_e32 v13, v3
	v_readlane_b32 s37, v243, 33
	v_readlane_b32 s38, v243, 34
	v_readlane_b32 s39, v243, 35
	v_readlane_b32 s40, v243, 36
	v_readlane_b32 s41, v243, 37
	v_readlane_b32 s42, v243, 38
	v_readlane_b32 s43, v243, 39
	v_readlane_b32 s44, v243, 40
	v_readlane_b32 s45, v243, 41
	v_readlane_b32 s46, v243, 42
	v_readlane_b32 s47, v243, 43
	s_branch .LBB0_436

;     __device__ bool next(int i, Unit& u) const { if (i != 0) return false; return so.next(round, u); }
;     __device__ __forceinline__ bool next(int i, Unit& u) const { if (i > 0 || !on) return false; u.pm = pm; u.pn = 0; return true; }
;     __host__ __device__ bool next(int i, Unit& u) const {
;         const long L = (long)i * G + c; if (L >= nwg) return false;
;         int wgid = (int)L; { const int q = nwg / NXCD, r = nwg % NXCD, xcd = wgid % NXCD, off = wgid / NXCD; wgid = (xcd < r ? xcd * (q + 1) : r * (q + 1) + (xcd - r) * q) + off; }
;         const int nig = WGM * nN, gid = wgid / nig, fm = gid * WGM, gsz = (nM - fm) < WGM ? (nM - fm) : WGM;
;         u.pm = fm + ((wgid % nig) % gsz); u.pn = (wgid % nig) / gsz; return true;
.Lprio_p5:
	v_readlane_b32 s0, v243, 2
	s_cmpk_lt_i32 s0, 0x200
	v_mov_b32_e32 v1, v220
	s_cselect_b64 s[2:3], -1, 0
	s_cmpk_gt_i32 s0, 0x1ff
	s_waitcnt lgkmcnt(0)
	s_barrier
	s_cbranch_scc1 .LBB0_3850
	v_readlane_b32 s1, v243, 2
	s_ashr_i32 s33, s1, 31
	s_lshr_b32 s0, s33, 29
	s_add_i32 s5, s1, s0
	s_and_b32 s0, s5, -8
	s_sub_i32 s6, s1, s0
	s_cmp_gt_i32 s6, -1
	s_cbranch_scc0 .LBB0_3827
	s_lshl_b32 s4, s6, 6
	s_cbranch_execz .LBB0_3828
	s_branch .LBB0_3829
